# prep phase: static s_setprio 1 for the second half-workgroup (waves 4-7) for the whole phase, reset at phase exit; on top of the static GEMM priority
# baseline (speedup 1.0000x reference)
.LBB0_564:
	s_andn2_b64 vcc, exec, s[2:3]
	s_cbranch_vccnz .LBB0_687
	s_cmp_lt_i32 s57, 1
	s_mov_b64 s[2:3], -1
	s_cbranch_scc1 .LBB0_678
	s_cmp_gt_i32 s57, 1
	s_cbranch_scc0 .LBB0_664
	v_readfirstlane_b32 s100, v158
	s_lshr_b32 s100, s100, 8
	s_cmp_eq_u32 s100, 1
	s_cbranch_scc0 .Lprio_prep
	s_setprio 1

.LBB0_663:
	s_setprio 0
	v_readlane_b32 s56, v255, 8
	v_readlane_b32 s88, v254, 63
	v_readlane_b32 s84, v255, 10
	v_readlane_b32 s80, v255, 1
	v_readlane_b32 s82, v255, 16
	v_readlane_b32 s54, v255, 3
	v_readlane_b32 s57, v255, 9
	s_mov_b64 s[2:3], 0
	v_readlane_b32 s89, v255, 0
	v_readlane_b32 s85, v255, 11
	v_readlane_b32 s86, v255, 12
	v_readlane_b32 s87, v255, 13
	v_readlane_b32 s81, v255, 2
	v_readlane_b32 s83, v255, 17
	s_movk_i32 s68, 0x3ff
	s_mov_b32 s69, 0x10000
	s_movk_i32 s70, 0x7fff
	s_movk_i32 s71, 0xb00
	s_movk_i32 s90, 0xc0
	s_mov_b32 s73, 0xb000
	s_movk_i32 s78, 0x80
	s_mov_b32 s79, 0x40000
	s_mov_b32 s91, 0x48000
	s_mov_b32 s92, 0x50000
	s_mov_b32 s93, 0xba2e8ba3
	s_mov_b32 s94, 0x2e8ba2e8
	s_mov_b32 s95, 0x3fb8aa3b
	s_mov_b32 s63, 0x78787879
	s_mov_b32 s64, 0xc2ce8ed0
	s_mov_b32 s65, 0x42b17218
	s_movk_i32 s58, 0x15ff
	s_movk_i32 s27, 0x5ff
	v_readlane_b32 s28, v254, 62
	v_readlane_b32 s55, v255, 4
	s_mov_b32 s57, s31
	v_readlane_b32 s44, v255, 5
	v_readlane_b32 s45, v255, 6
